# v23 + A-GEMM and B-GEMM StoreBf16 epilogues with a DPP row exchange so every store writes 8 rows x 128 contiguous bytes (full cache lines)
# speedup vs baseline: 1.0015x; 1.0007x over previous
; __device__ __forceinline__ unsigned pk2(float lo, float hi) { f32x2 v = {lo, hi}; bf2_t b = __builtin_convertvector(v, bf2_t); return __builtin_bit_cast(unsigned, b); }
;     __device__ __forceinline__ void operator()(const AccT& acc, const Unit& u, int wr, int wc, int fr, int fq) const {
;         const int row0 = u.pm * 256 + wr * 64 + fr, col0 = u.pn * 256 + wc * 64 + 16 * fq;
; #pragma unroll
;         for (int ai = 0; ai < 2; ++ai)
; #pragma unroll
;             for (int m = 0; m < 4; ++m) {
;                 u32x4 w[2];
; #pragma unroll
;                 for (int bj = 0; bj < 2; ++bj) { w[bj].x = pk2(acc[ai][bj][m][0][0], acc[ai][bj][m][0][1]); w[bj].y = pk2(acc[ai][bj][m][0][2], acc[ai][bj][m][0][3]); w[bj].z = pk2(acc[ai][bj][m][1][0], acc[ai][bj][m][1][1]); w[bj].w = pk2(acc[ai][bj][m][1][2], acc[ai][bj][m][1][3]); }
;                 u32x4* op = (u32x4*)(T + (size_t)(row0 + ai * 128 + m * 16) * DM + col0); op[0] = w[0]; op[1] = w[1];
;             }
;     }
.LBB0_784:
	v_lshl_add_u32 v142, s38, 8, v138
	v_lshl_or_b32 v144, s37, 8, v140
	v_and_b32_e32 v146, 7, v138
	v_bfe_u32 v147, v138, 3, 1
	v_and_b32_e32 v148, -16, v142
	v_add_u32_e32 v148, v148, v146
	v_ashrrev_i32_e32 v149, 31, v148
	v_lshlrev_b64 v[148:149], 11, v[148:149]
	v_lshl_add_u64 v[148:149], s[6:7], 0, v[148:149]
	v_lshlrev_b32_e32 v150, 1, v144
	v_lshl_add_u32 v150, v147, 4, v150
	v_mov_b32_e32 v151, v189
	v_lshl_add_u64 v[148:149], v[148:149], 0, v[150:151]
	v_cvt_pk_bf16_f32 v152, v124, v125
	v_cvt_pk_bf16_f32 v153, v126, v127
	v_cvt_pk_bf16_f32 v154, v120, v121
	v_cvt_pk_bf16_f32 v155, v122, v123
	v_cvt_pk_bf16_f32 v156, v112, v113
	v_cvt_pk_bf16_f32 v157, v114, v115
	v_cvt_pk_bf16_f32 v158, v104, v105
	v_cvt_pk_bf16_f32 v159, v106, v107
	v_mov_b32_e32 v160, v156
	v_mov_b32_e32 v161, v157
	v_mov_b32_e32 v162, v158
	v_mov_b32_e32 v163, v159
	v_mov_b64_e32 v[176:177], v[148:149]
	s_mov_b64 s[52:53], 0x4000
	v_lshl_add_u64 v[178:179], v[148:149], 0, s[52:53]
	v_mov_b32_dpp v156, v152 row_ror:8 row_mask:0xf bank_mask:0x3
	v_mov_b32_dpp v157, v153 row_ror:8 row_mask:0xf bank_mask:0x3
	v_mov_b32_dpp v158, v154 row_ror:8 row_mask:0xf bank_mask:0x3
	v_mov_b32_dpp v159, v155 row_ror:8 row_mask:0xf bank_mask:0x3
	v_mov_b32_dpp v152, v160 row_ror:8 row_mask:0xf bank_mask:0xc
	v_mov_b32_dpp v153, v161 row_ror:8 row_mask:0xf bank_mask:0xc
	v_mov_b32_dpp v154, v162 row_ror:8 row_mask:0xf bank_mask:0xc
	v_mov_b32_dpp v155, v163 row_ror:8 row_mask:0xf bank_mask:0xc
	s_nop 0
	global_store_dwordx4 v[176:177], v[152:155], off
	global_store_dwordx4 v[178:179], v[156:159], off
	v_cvt_pk_bf16_f32 v164, v116, v117
	v_cvt_pk_bf16_f32 v165, v118, v119
	v_cvt_pk_bf16_f32 v166, v108, v109
	v_cvt_pk_bf16_f32 v167, v110, v111
	v_cvt_pk_bf16_f32 v168, v92, v93
	v_cvt_pk_bf16_f32 v169, v94, v95
	v_cvt_pk_bf16_f32 v170, v88, v89
	v_cvt_pk_bf16_f32 v171, v90, v91
	v_mov_b32_e32 v172, v168
	v_mov_b32_e32 v173, v169
	v_mov_b32_e32 v174, v170
	v_mov_b32_e32 v175, v171
	s_mov_b64 s[52:53], 0x8000
	v_lshl_add_u64 v[176:177], v[148:149], 0, s[52:53]
	s_mov_b64 s[52:53], 0xc000
	v_lshl_add_u64 v[178:179], v[148:149], 0, s[52:53]
	v_mov_b32_dpp v168, v164 row_ror:8 row_mask:0xf bank_mask:0x3
	v_mov_b32_dpp v169, v165 row_ror:8 row_mask:0xf bank_mask:0x3
	v_mov_b32_dpp v170, v166 row_ror:8 row_mask:0xf bank_mask:0x3
	v_mov_b32_dpp v171, v167 row_ror:8 row_mask:0xf bank_mask:0x3
	v_mov_b32_dpp v164, v172 row_ror:8 row_mask:0xf bank_mask:0xc
	v_mov_b32_dpp v165, v173 row_ror:8 row_mask:0xf bank_mask:0xc
	v_mov_b32_dpp v166, v174 row_ror:8 row_mask:0xf bank_mask:0xc
	v_mov_b32_dpp v167, v175 row_ror:8 row_mask:0xf bank_mask:0xc
	s_nop 0
	global_store_dwordx4 v[176:177], v[164:167], off
	global_store_dwordx4 v[178:179], v[168:171], off
	v_cvt_pk_bf16_f32 v152, v100, v101
	v_cvt_pk_bf16_f32 v153, v102, v103
	v_cvt_pk_bf16_f32 v154, v96, v97
	v_cvt_pk_bf16_f32 v155, v98, v99
	v_cvt_pk_bf16_f32 v156, v76, v77
	v_cvt_pk_bf16_f32 v157, v78, v79
	v_cvt_pk_bf16_f32 v158, v72, v73
	v_cvt_pk_bf16_f32 v159, v74, v75
	v_mov_b32_e32 v160, v156
	v_mov_b32_e32 v161, v157
	v_mov_b32_e32 v162, v158
	v_mov_b32_e32 v163, v159
	s_mov_b64 s[52:53], 0x10000
	v_lshl_add_u64 v[176:177], v[148:149], 0, s[52:53]
	s_mov_b64 s[52:53], 0x14000
	v_lshl_add_u64 v[178:179], v[148:149], 0, s[52:53]
	v_mov_b32_dpp v156, v152 row_ror:8 row_mask:0xf bank_mask:0x3
	v_mov_b32_dpp v157, v153 row_ror:8 row_mask:0xf bank_mask:0x3
	v_mov_b32_dpp v158, v154 row_ror:8 row_mask:0xf bank_mask:0x3
	v_mov_b32_dpp v159, v155 row_ror:8 row_mask:0xf bank_mask:0x3
	v_mov_b32_dpp v152, v160 row_ror:8 row_mask:0xf bank_mask:0xc
	v_mov_b32_dpp v153, v161 row_ror:8 row_mask:0xf bank_mask:0xc
	v_mov_b32_dpp v154, v162 row_ror:8 row_mask:0xf bank_mask:0xc
	v_mov_b32_dpp v155, v163 row_ror:8 row_mask:0xf bank_mask:0xc
	s_nop 0
	global_store_dwordx4 v[176:177], v[152:155], off
	global_store_dwordx4 v[178:179], v[156:159], off
	v_cvt_pk_bf16_f32 v164, v84, v85
	v_cvt_pk_bf16_f32 v165, v86, v87
	v_cvt_pk_bf16_f32 v166, v80, v81
	v_cvt_pk_bf16_f32 v167, v82, v83
	v_cvt_pk_bf16_f32 v168, v68, v69
	v_cvt_pk_bf16_f32 v169, v70, v71
	v_cvt_pk_bf16_f32 v170, v64, v65
	v_cvt_pk_bf16_f32 v171, v66, v67
	v_mov_b32_e32 v172, v168
	v_mov_b32_e32 v173, v169
	v_mov_b32_e32 v174, v170
	v_mov_b32_e32 v175, v171
	s_mov_b64 s[52:53], 0x18000
	v_lshl_add_u64 v[176:177], v[148:149], 0, s[52:53]
	s_mov_b64 s[52:53], 0x1c000
	v_lshl_add_u64 v[178:179], v[148:149], 0, s[52:53]
	v_mov_b32_dpp v168, v164 row_ror:8 row_mask:0xf bank_mask:0x3
	v_mov_b32_dpp v169, v165 row_ror:8 row_mask:0xf bank_mask:0x3
	v_mov_b32_dpp v170, v166 row_ror:8 row_mask:0xf bank_mask:0x3
	v_mov_b32_dpp v171, v167 row_ror:8 row_mask:0xf bank_mask:0x3
	v_mov_b32_dpp v164, v172 row_ror:8 row_mask:0xf bank_mask:0xc
	v_mov_b32_dpp v165, v173 row_ror:8 row_mask:0xf bank_mask:0xc
	v_mov_b32_dpp v166, v174 row_ror:8 row_mask:0xf bank_mask:0xc
; __device__ __forceinline__ unsigned pk2(float lo, float hi) { f32x2 v = {lo, hi}; bf2_t b = __builtin_convertvector(v, bf2_t); return __builtin_bit_cast(unsigned, b); }
; #define PG8_BAR __builtin_amdgcn_s_barrier()
; template <class Epi, class Sched>
; __device__ __forceinline__ void gemm_phase(int wv, LAS unsigned char* lds, const Gemm g, const Sched& S, const Epi& E) {
;     ...
;         if (wr == 0) PG8_BAR;
;         E(acc, cur, wr, wc, fr, fq);
;         if (!has_next) break;
; #pragma unroll
;         for (int a = 0; a < 2; ++a)
; #pragma unroll
;             for (int b = 0; b < 2; ++b)
; #pragma unroll
;                 for (int m = 0; m < 4; ++m)
; #pragma unroll
;                     for (int n = 0; n < 2; ++n) acc[a][b][m][n] = (f32x4){0.f, 0.f, 0.f, 0.f};
;         cur = nxt; cA = nA; cB = nB; ++ui;
;         if (wr == 1) PG8_BAR;
;     }
;     __device__ __forceinline__ void operator()(const AccT& acc, const Unit& u, int wr, int wc, int fr, int fq) const {
;         const int row0 = u.pm * 256 + wr * 64 + fr, col0 = u.pn * 256 + wc * 64 + 16 * fq;
; #pragma unroll
;         for (int ai = 0; ai < 2; ++ai)
; #pragma unroll
;             for (int m = 0; m < 4; ++m) {
;                 u32x4 w[2];
; #pragma unroll
;                 for (int bj = 0; bj < 2; ++bj) { w[bj].x = pk2(acc[ai][bj][m][0][0], acc[ai][bj][m][0][1]); w[bj].y = pk2(acc[ai][bj][m][0][2], acc[ai][bj][m][0][3]); w[bj].z = pk2(acc[ai][bj][m][1][0], acc[ai][bj][m][1][1]); w[bj].w = pk2(acc[ai][bj][m][1][2], acc[ai][bj][m][1][3]); }
;                 u32x4* op = (u32x4*)(T + (size_t)(row0 + ai * 128 + m * 16) * DM + col0); op[0] = w[0]; op[1] = w[1];
;             }
;     }
	v_mov_b32_dpp v167, v175 row_ror:8 row_mask:0xf bank_mask:0xc
	s_nop 0
	global_store_dwordx4 v[176:177], v[164:167], off
	global_store_dwordx4 v[178:179], v[168:171], off
	v_cvt_pk_bf16_f32 v152, v60, v61
	v_cvt_pk_bf16_f32 v153, v62, v63
	v_cvt_pk_bf16_f32 v154, v56, v57
	v_cvt_pk_bf16_f32 v155, v58, v59
	v_cvt_pk_bf16_f32 v156, v44, v45
	v_cvt_pk_bf16_f32 v157, v46, v47
	v_cvt_pk_bf16_f32 v158, v40, v41
	v_cvt_pk_bf16_f32 v159, v42, v43
	v_mov_b32_e32 v160, v156
	v_mov_b32_e32 v161, v157
	v_mov_b32_e32 v162, v158
	v_mov_b32_e32 v163, v159
	s_mov_b64 s[52:53], 0x40000
	v_lshl_add_u64 v[176:177], v[148:149], 0, s[52:53]
	s_mov_b64 s[52:53], 0x44000
	v_lshl_add_u64 v[178:179], v[148:149], 0, s[52:53]
	v_mov_b32_dpp v156, v152 row_ror:8 row_mask:0xf bank_mask:0x3
	v_mov_b32_dpp v157, v153 row_ror:8 row_mask:0xf bank_mask:0x3
	v_mov_b32_dpp v158, v154 row_ror:8 row_mask:0xf bank_mask:0x3
	v_mov_b32_dpp v159, v155 row_ror:8 row_mask:0xf bank_mask:0x3
	v_mov_b32_dpp v152, v160 row_ror:8 row_mask:0xf bank_mask:0xc
	v_mov_b32_dpp v153, v161 row_ror:8 row_mask:0xf bank_mask:0xc
	v_mov_b32_dpp v154, v162 row_ror:8 row_mask:0xf bank_mask:0xc
	v_mov_b32_dpp v155, v163 row_ror:8 row_mask:0xf bank_mask:0xc
	s_nop 0
	global_store_dwordx4 v[176:177], v[152:155], off
	global_store_dwordx4 v[178:179], v[156:159], off
	v_cvt_pk_bf16_f32 v164, v52, v53
	v_cvt_pk_bf16_f32 v165, v54, v55
	v_cvt_pk_bf16_f32 v166, v48, v49
	v_cvt_pk_bf16_f32 v167, v50, v51
	v_cvt_pk_bf16_f32 v168, v28, v29
	v_cvt_pk_bf16_f32 v169, v30, v31
	v_cvt_pk_bf16_f32 v170, v24, v25
	v_cvt_pk_bf16_f32 v171, v26, v27
	v_mov_b32_e32 v172, v168
	v_mov_b32_e32 v173, v169
	v_mov_b32_e32 v174, v170
	v_mov_b32_e32 v175, v171
	s_mov_b64 s[52:53], 0x48000
	v_lshl_add_u64 v[176:177], v[148:149], 0, s[52:53]
	s_mov_b64 s[52:53], 0x4c000
	v_lshl_add_u64 v[178:179], v[148:149], 0, s[52:53]
	v_mov_b32_dpp v168, v164 row_ror:8 row_mask:0xf bank_mask:0x3
	v_mov_b32_dpp v169, v165 row_ror:8 row_mask:0xf bank_mask:0x3
	v_mov_b32_dpp v170, v166 row_ror:8 row_mask:0xf bank_mask:0x3
	v_mov_b32_dpp v171, v167 row_ror:8 row_mask:0xf bank_mask:0x3
	v_mov_b32_dpp v164, v172 row_ror:8 row_mask:0xf bank_mask:0xc
	v_mov_b32_dpp v165, v173 row_ror:8 row_mask:0xf bank_mask:0xc
	v_mov_b32_dpp v166, v174 row_ror:8 row_mask:0xf bank_mask:0xc
	v_mov_b32_dpp v167, v175 row_ror:8 row_mask:0xf bank_mask:0xc
	s_nop 0
	global_store_dwordx4 v[176:177], v[164:167], off
	global_store_dwordx4 v[178:179], v[168:171], off
	v_cvt_pk_bf16_f32 v152, v36, v37
	v_cvt_pk_bf16_f32 v153, v38, v39
	v_cvt_pk_bf16_f32 v154, v32, v33
	v_cvt_pk_bf16_f32 v155, v34, v35
	v_cvt_pk_bf16_f32 v156, v12, v13
	v_cvt_pk_bf16_f32 v157, v14, v15
	v_cvt_pk_bf16_f32 v158, v8, v9
	v_cvt_pk_bf16_f32 v159, v10, v11
	v_mov_b32_e32 v160, v156
	v_mov_b32_e32 v161, v157
	v_mov_b32_e32 v162, v158
	v_mov_b32_e32 v163, v159
	s_mov_b64 s[52:53], 0x50000
	v_lshl_add_u64 v[176:177], v[148:149], 0, s[52:53]
	s_mov_b64 s[52:53], 0x54000
	v_lshl_add_u64 v[178:179], v[148:149], 0, s[52:53]
	v_mov_b32_dpp v156, v152 row_ror:8 row_mask:0xf bank_mask:0x3
	v_mov_b32_dpp v157, v153 row_ror:8 row_mask:0xf bank_mask:0x3
	v_mov_b32_dpp v158, v154 row_ror:8 row_mask:0xf bank_mask:0x3
	v_mov_b32_dpp v159, v155 row_ror:8 row_mask:0xf bank_mask:0x3
	v_mov_b32_dpp v152, v160 row_ror:8 row_mask:0xf bank_mask:0xc
	v_mov_b32_dpp v153, v161 row_ror:8 row_mask:0xf bank_mask:0xc
	v_mov_b32_dpp v154, v162 row_ror:8 row_mask:0xf bank_mask:0xc
	v_mov_b32_dpp v155, v163 row_ror:8 row_mask:0xf bank_mask:0xc
	s_nop 0
	global_store_dwordx4 v[176:177], v[152:155], off
	global_store_dwordx4 v[178:179], v[156:159], off
	v_cvt_pk_bf16_f32 v164, v20, v21
	v_cvt_pk_bf16_f32 v165, v22, v23
	v_cvt_pk_bf16_f32 v166, v16, v17
	v_cvt_pk_bf16_f32 v167, v18, v19
	v_cvt_pk_bf16_f32 v168, v4, v5
	v_cvt_pk_bf16_f32 v169, v6, v7
	v_cvt_pk_bf16_f32 v170, v0, v1
	v_cvt_pk_bf16_f32 v171, v2, v3
	v_mov_b32_e32 v172, v168
	v_mov_b32_e32 v173, v169
	v_mov_b32_e32 v174, v170
	v_mov_b32_e32 v175, v171
	s_mov_b64 s[52:53], 0x58000
	v_lshl_add_u64 v[176:177], v[148:149], 0, s[52:53]
	s_mov_b64 s[52:53], 0x5c000
	v_lshl_add_u64 v[178:179], v[148:149], 0, s[52:53]
	v_mov_b32_dpp v168, v164 row_ror:8 row_mask:0xf bank_mask:0x3
	v_mov_b32_dpp v169, v165 row_ror:8 row_mask:0xf bank_mask:0x3
	v_mov_b32_dpp v170, v166 row_ror:8 row_mask:0xf bank_mask:0x3
	v_mov_b32_dpp v171, v167 row_ror:8 row_mask:0xf bank_mask:0x3
	v_mov_b32_dpp v164, v172 row_ror:8 row_mask:0xf bank_mask:0xc
	v_mov_b32_dpp v165, v173 row_ror:8 row_mask:0xf bank_mask:0xc
	v_mov_b32_dpp v166, v174 row_ror:8 row_mask:0xf bank_mask:0xc
	v_mov_b32_dpp v167, v175 row_ror:8 row_mask:0xf bank_mask:0xc
	s_nop 0
	global_store_dwordx4 v[176:177], v[164:167], off
	global_store_dwordx4 v[178:179], v[168:171], off
	s_andn2_b64 vcc, exec, s[2:3]
	s_mov_b64 s[2:3], -1
	s_cbranch_vccnz .LBB0_773
	s_andn2_b64 vcc, exec, s[8:9]
	s_cbranch_vccnz .LBB0_772
	s_barrier
	s_branch .LBB0_772

; __device__ __forceinline__ unsigned pk2(float lo, float hi) { f32x2 v = {lo, hi}; bf2_t b = __builtin_convertvector(v, bf2_t); return __builtin_bit_cast(unsigned, b); }
;     __device__ __forceinline__ void operator()(const AccT& acc, const Unit& u, int wr, int wc, int fr, int fq) const {
;         const int row0 = u.pm * 256 + wr * 64 + fr, col0 = u.pn * 256 + wc * 64 + 16 * fq;
; #pragma unroll
;         for (int ai = 0; ai < 2; ++ai)
; #pragma unroll
;             for (int m = 0; m < 4; ++m) {
;                 u32x4 w[2];
; #pragma unroll
;                 for (int bj = 0; bj < 2; ++bj) { w[bj].x = pk2(acc[ai][bj][m][0][0], acc[ai][bj][m][0][1]); w[bj].y = pk2(acc[ai][bj][m][0][2], acc[ai][bj][m][0][3]); w[bj].z = pk2(acc[ai][bj][m][1][0], acc[ai][bj][m][1][1]); w[bj].w = pk2(acc[ai][bj][m][1][2], acc[ai][bj][m][1][3]); }
;                 u32x4* op = (u32x4*)(T + (size_t)(row0 + ai * 128 + m * 16) * DM + col0); op[0] = w[0]; op[1] = w[1];
;             }
;     }
.LBB0_804:
	v_lshl_add_u32 v142, s38, 8, v138
	v_lshl_or_b32 v144, s37, 8, v140
	v_and_b32_e32 v146, 7, v138
	v_bfe_u32 v147, v138, 3, 1
	v_and_b32_e32 v148, -16, v142
	v_add_u32_e32 v148, v148, v146
	v_ashrrev_i32_e32 v149, 31, v148
	v_lshlrev_b64 v[148:149], 11, v[148:149]
	v_lshl_add_u64 v[148:149], s[6:7], 0, v[148:149]
	v_lshlrev_b32_e32 v150, 1, v144
	v_lshl_add_u32 v150, v147, 4, v150
	v_mov_b32_e32 v151, v189
	v_lshl_add_u64 v[148:149], v[148:149], 0, v[150:151]
	v_cvt_pk_bf16_f32 v152, v124, v125
	v_cvt_pk_bf16_f32 v153, v126, v127
	v_cvt_pk_bf16_f32 v154, v120, v121
	v_cvt_pk_bf16_f32 v155, v122, v123
	v_cvt_pk_bf16_f32 v156, v112, v113
	v_cvt_pk_bf16_f32 v157, v114, v115
	v_cvt_pk_bf16_f32 v158, v104, v105
	v_cvt_pk_bf16_f32 v159, v106, v107
	v_mov_b32_e32 v160, v156
	v_mov_b32_e32 v161, v157
	v_mov_b32_e32 v162, v158
	v_mov_b32_e32 v163, v159
	v_mov_b64_e32 v[176:177], v[148:149]
	s_mov_b64 s[52:53], 0x4000
	v_lshl_add_u64 v[178:179], v[148:149], 0, s[52:53]
	v_mov_b32_dpp v156, v152 row_ror:8 row_mask:0xf bank_mask:0x3
	v_mov_b32_dpp v157, v153 row_ror:8 row_mask:0xf bank_mask:0x3
	v_mov_b32_dpp v158, v154 row_ror:8 row_mask:0xf bank_mask:0x3
	v_mov_b32_dpp v159, v155 row_ror:8 row_mask:0xf bank_mask:0x3
	v_mov_b32_dpp v152, v160 row_ror:8 row_mask:0xf bank_mask:0xc
	v_mov_b32_dpp v153, v161 row_ror:8 row_mask:0xf bank_mask:0xc
	v_mov_b32_dpp v154, v162 row_ror:8 row_mask:0xf bank_mask:0xc
	v_mov_b32_dpp v155, v163 row_ror:8 row_mask:0xf bank_mask:0xc
	s_nop 0
	global_store_dwordx4 v[176:177], v[152:155], off
	global_store_dwordx4 v[178:179], v[156:159], off
	v_cvt_pk_bf16_f32 v164, v116, v117
	v_cvt_pk_bf16_f32 v165, v118, v119
	v_cvt_pk_bf16_f32 v166, v108, v109
	v_cvt_pk_bf16_f32 v167, v110, v111
	v_cvt_pk_bf16_f32 v168, v92, v93
	v_cvt_pk_bf16_f32 v169, v94, v95
	v_cvt_pk_bf16_f32 v170, v88, v89
	v_cvt_pk_bf16_f32 v171, v90, v91
	v_mov_b32_e32 v172, v168
	v_mov_b32_e32 v173, v169
	v_mov_b32_e32 v174, v170
	v_mov_b32_e32 v175, v171
	s_mov_b64 s[52:53], 0x8000
	v_lshl_add_u64 v[176:177], v[148:149], 0, s[52:53]
	s_mov_b64 s[52:53], 0xc000
	v_lshl_add_u64 v[178:179], v[148:149], 0, s[52:53]
	v_mov_b32_dpp v168, v164 row_ror:8 row_mask:0xf bank_mask:0x3
	v_mov_b32_dpp v169, v165 row_ror:8 row_mask:0xf bank_mask:0x3
	v_mov_b32_dpp v170, v166 row_ror:8 row_mask:0xf bank_mask:0x3
	v_mov_b32_dpp v171, v167 row_ror:8 row_mask:0xf bank_mask:0x3
	v_mov_b32_dpp v164, v172 row_ror:8 row_mask:0xf bank_mask:0xc
	v_mov_b32_dpp v165, v173 row_ror:8 row_mask:0xf bank_mask:0xc
	v_mov_b32_dpp v166, v174 row_ror:8 row_mask:0xf bank_mask:0xc
	v_mov_b32_dpp v167, v175 row_ror:8 row_mask:0xf bank_mask:0xc
	s_nop 0
	global_store_dwordx4 v[176:177], v[164:167], off
	global_store_dwordx4 v[178:179], v[168:171], off
	v_cvt_pk_bf16_f32 v152, v100, v101
	v_cvt_pk_bf16_f32 v153, v102, v103
	v_cvt_pk_bf16_f32 v154, v96, v97
	v_cvt_pk_bf16_f32 v155, v98, v99
	v_cvt_pk_bf16_f32 v156, v76, v77
	v_cvt_pk_bf16_f32 v157, v78, v79
	v_cvt_pk_bf16_f32 v158, v72, v73
	v_cvt_pk_bf16_f32 v159, v74, v75
	v_mov_b32_e32 v160, v156
	v_mov_b32_e32 v161, v157
	v_mov_b32_e32 v162, v158
	v_mov_b32_e32 v163, v159
	s_mov_b64 s[52:53], 0x10000
	v_lshl_add_u64 v[176:177], v[148:149], 0, s[52:53]
	s_mov_b64 s[52:53], 0x14000
	v_lshl_add_u64 v[178:179], v[148:149], 0, s[52:53]
	v_mov_b32_dpp v156, v152 row_ror:8 row_mask:0xf bank_mask:0x3
	v_mov_b32_dpp v157, v153 row_ror:8 row_mask:0xf bank_mask:0x3
	v_mov_b32_dpp v158, v154 row_ror:8 row_mask:0xf bank_mask:0x3
	v_mov_b32_dpp v159, v155 row_ror:8 row_mask:0xf bank_mask:0x3
	v_mov_b32_dpp v152, v160 row_ror:8 row_mask:0xf bank_mask:0xc
	v_mov_b32_dpp v153, v161 row_ror:8 row_mask:0xf bank_mask:0xc
	v_mov_b32_dpp v154, v162 row_ror:8 row_mask:0xf bank_mask:0xc
	v_mov_b32_dpp v155, v163 row_ror:8 row_mask:0xf bank_mask:0xc
	s_nop 0
	global_store_dwordx4 v[176:177], v[152:155], off
	global_store_dwordx4 v[178:179], v[156:159], off
	v_cvt_pk_bf16_f32 v164, v84, v85
	v_cvt_pk_bf16_f32 v165, v86, v87
	v_cvt_pk_bf16_f32 v166, v80, v81
	v_cvt_pk_bf16_f32 v167, v82, v83
	v_cvt_pk_bf16_f32 v168, v68, v69
	v_cvt_pk_bf16_f32 v169, v70, v71
	v_cvt_pk_bf16_f32 v170, v64, v65
	v_cvt_pk_bf16_f32 v171, v66, v67
	v_mov_b32_e32 v172, v168
	v_mov_b32_e32 v173, v169
	v_mov_b32_e32 v174, v170
	v_mov_b32_e32 v175, v171
	s_mov_b64 s[52:53], 0x18000
	v_lshl_add_u64 v[176:177], v[148:149], 0, s[52:53]
	s_mov_b64 s[52:53], 0x1c000
	v_lshl_add_u64 v[178:179], v[148:149], 0, s[52:53]
	v_mov_b32_dpp v168, v164 row_ror:8 row_mask:0xf bank_mask:0x3
	v_mov_b32_dpp v169, v165 row_ror:8 row_mask:0xf bank_mask:0x3
	v_mov_b32_dpp v170, v166 row_ror:8 row_mask:0xf bank_mask:0x3
	v_mov_b32_dpp v171, v167 row_ror:8 row_mask:0xf bank_mask:0x3
	v_mov_b32_dpp v164, v172 row_ror:8 row_mask:0xf bank_mask:0xc
	v_mov_b32_dpp v165, v173 row_ror:8 row_mask:0xf bank_mask:0xc
	v_mov_b32_dpp v166, v174 row_ror:8 row_mask:0xf bank_mask:0xc
; __device__ __forceinline__ unsigned pk2(float lo, float hi) { f32x2 v = {lo, hi}; bf2_t b = __builtin_convertvector(v, bf2_t); return __builtin_bit_cast(unsigned, b); }
; #define PG8_BAR __builtin_amdgcn_s_barrier()
; template <class Epi, class Sched>
; __device__ __forceinline__ void gemm_phase(int wv, LAS unsigned char* lds, const Gemm g, const Sched& S, const Epi& E) {
;     ...
;         if (wr == 0) PG8_BAR;
;         E(acc, cur, wr, wc, fr, fq);
;         if (!has_next) break;
; #pragma unroll
;         for (int a = 0; a < 2; ++a)
; #pragma unroll
;             for (int b = 0; b < 2; ++b)
; #pragma unroll
;                 for (int m = 0; m < 4; ++m)
; #pragma unroll
;                     for (int n = 0; n < 2; ++n) acc[a][b][m][n] = (f32x4){0.f, 0.f, 0.f, 0.f};
;         cur = nxt; cA = nA; cB = nB; ++ui;
;         if (wr == 1) PG8_BAR;
;     }
;     __device__ __forceinline__ void operator()(const AccT& acc, const Unit& u, int wr, int wc, int fr, int fq) const {
;         const int row0 = u.pm * 256 + wr * 64 + fr, col0 = u.pn * 256 + wc * 64 + 16 * fq;
; #pragma unroll
;         for (int ai = 0; ai < 2; ++ai)
; #pragma unroll
;             for (int m = 0; m < 4; ++m) {
;                 u32x4 w[2];
; #pragma unroll
;                 for (int bj = 0; bj < 2; ++bj) { w[bj].x = pk2(acc[ai][bj][m][0][0], acc[ai][bj][m][0][1]); w[bj].y = pk2(acc[ai][bj][m][0][2], acc[ai][bj][m][0][3]); w[bj].z = pk2(acc[ai][bj][m][1][0], acc[ai][bj][m][1][1]); w[bj].w = pk2(acc[ai][bj][m][1][2], acc[ai][bj][m][1][3]); }
;                 u32x4* op = (u32x4*)(T + (size_t)(row0 + ai * 128 + m * 16) * DM + col0); op[0] = w[0]; op[1] = w[1];
;             }
;     }
	v_mov_b32_dpp v167, v175 row_ror:8 row_mask:0xf bank_mask:0xc
	s_nop 0
	global_store_dwordx4 v[176:177], v[164:167], off
	global_store_dwordx4 v[178:179], v[168:171], off
	v_cvt_pk_bf16_f32 v152, v60, v61
	v_cvt_pk_bf16_f32 v153, v62, v63
	v_cvt_pk_bf16_f32 v154, v56, v57
	v_cvt_pk_bf16_f32 v155, v58, v59
	v_cvt_pk_bf16_f32 v156, v44, v45
	v_cvt_pk_bf16_f32 v157, v46, v47
	v_cvt_pk_bf16_f32 v158, v40, v41
	v_cvt_pk_bf16_f32 v159, v42, v43
	v_mov_b32_e32 v160, v156
	v_mov_b32_e32 v161, v157
	v_mov_b32_e32 v162, v158
	v_mov_b32_e32 v163, v159
	s_mov_b64 s[52:53], 0x40000
	v_lshl_add_u64 v[176:177], v[148:149], 0, s[52:53]
	s_mov_b64 s[52:53], 0x44000
	v_lshl_add_u64 v[178:179], v[148:149], 0, s[52:53]
	v_mov_b32_dpp v156, v152 row_ror:8 row_mask:0xf bank_mask:0x3
	v_mov_b32_dpp v157, v153 row_ror:8 row_mask:0xf bank_mask:0x3
	v_mov_b32_dpp v158, v154 row_ror:8 row_mask:0xf bank_mask:0x3
	v_mov_b32_dpp v159, v155 row_ror:8 row_mask:0xf bank_mask:0x3
	v_mov_b32_dpp v152, v160 row_ror:8 row_mask:0xf bank_mask:0xc
	v_mov_b32_dpp v153, v161 row_ror:8 row_mask:0xf bank_mask:0xc
	v_mov_b32_dpp v154, v162 row_ror:8 row_mask:0xf bank_mask:0xc
	v_mov_b32_dpp v155, v163 row_ror:8 row_mask:0xf bank_mask:0xc
	s_nop 0
	global_store_dwordx4 v[176:177], v[152:155], off
	global_store_dwordx4 v[178:179], v[156:159], off
	v_cvt_pk_bf16_f32 v164, v52, v53
	v_cvt_pk_bf16_f32 v165, v54, v55
	v_cvt_pk_bf16_f32 v166, v48, v49
	v_cvt_pk_bf16_f32 v167, v50, v51
	v_cvt_pk_bf16_f32 v168, v28, v29
	v_cvt_pk_bf16_f32 v169, v30, v31
	v_cvt_pk_bf16_f32 v170, v24, v25
	v_cvt_pk_bf16_f32 v171, v26, v27
	v_mov_b32_e32 v172, v168
	v_mov_b32_e32 v173, v169
	v_mov_b32_e32 v174, v170
	v_mov_b32_e32 v175, v171
	s_mov_b64 s[52:53], 0x48000
	v_lshl_add_u64 v[176:177], v[148:149], 0, s[52:53]
	s_mov_b64 s[52:53], 0x4c000
	v_lshl_add_u64 v[178:179], v[148:149], 0, s[52:53]
	v_mov_b32_dpp v168, v164 row_ror:8 row_mask:0xf bank_mask:0x3
	v_mov_b32_dpp v169, v165 row_ror:8 row_mask:0xf bank_mask:0x3
	v_mov_b32_dpp v170, v166 row_ror:8 row_mask:0xf bank_mask:0x3
	v_mov_b32_dpp v171, v167 row_ror:8 row_mask:0xf bank_mask:0x3
	v_mov_b32_dpp v164, v172 row_ror:8 row_mask:0xf bank_mask:0xc
	v_mov_b32_dpp v165, v173 row_ror:8 row_mask:0xf bank_mask:0xc
	v_mov_b32_dpp v166, v174 row_ror:8 row_mask:0xf bank_mask:0xc
	v_mov_b32_dpp v167, v175 row_ror:8 row_mask:0xf bank_mask:0xc
	s_nop 0
	global_store_dwordx4 v[176:177], v[164:167], off
	global_store_dwordx4 v[178:179], v[168:171], off
	v_cvt_pk_bf16_f32 v152, v36, v37
	v_cvt_pk_bf16_f32 v153, v38, v39
	v_cvt_pk_bf16_f32 v154, v32, v33
	v_cvt_pk_bf16_f32 v155, v34, v35
	v_cvt_pk_bf16_f32 v156, v12, v13
	v_cvt_pk_bf16_f32 v157, v14, v15
	v_cvt_pk_bf16_f32 v158, v8, v9
	v_cvt_pk_bf16_f32 v159, v10, v11
	v_mov_b32_e32 v160, v156
	v_mov_b32_e32 v161, v157
	v_mov_b32_e32 v162, v158
	v_mov_b32_e32 v163, v159
	s_mov_b64 s[52:53], 0x50000
	v_lshl_add_u64 v[176:177], v[148:149], 0, s[52:53]
	s_mov_b64 s[52:53], 0x54000
	v_lshl_add_u64 v[178:179], v[148:149], 0, s[52:53]
	v_mov_b32_dpp v156, v152 row_ror:8 row_mask:0xf bank_mask:0x3
	v_mov_b32_dpp v157, v153 row_ror:8 row_mask:0xf bank_mask:0x3
	v_mov_b32_dpp v158, v154 row_ror:8 row_mask:0xf bank_mask:0x3
	v_mov_b32_dpp v159, v155 row_ror:8 row_mask:0xf bank_mask:0x3
	v_mov_b32_dpp v152, v160 row_ror:8 row_mask:0xf bank_mask:0xc
	v_mov_b32_dpp v153, v161 row_ror:8 row_mask:0xf bank_mask:0xc
	v_mov_b32_dpp v154, v162 row_ror:8 row_mask:0xf bank_mask:0xc
	v_mov_b32_dpp v155, v163 row_ror:8 row_mask:0xf bank_mask:0xc
	s_nop 0
	global_store_dwordx4 v[176:177], v[152:155], off
	global_store_dwordx4 v[178:179], v[156:159], off
	v_cvt_pk_bf16_f32 v164, v20, v21
	v_cvt_pk_bf16_f32 v165, v22, v23
	v_cvt_pk_bf16_f32 v166, v16, v17
	v_cvt_pk_bf16_f32 v167, v18, v19
	v_cvt_pk_bf16_f32 v168, v4, v5
	v_cvt_pk_bf16_f32 v169, v6, v7
	v_cvt_pk_bf16_f32 v170, v0, v1
	v_cvt_pk_bf16_f32 v171, v2, v3
	v_mov_b32_e32 v172, v168
	v_mov_b32_e32 v173, v169
	v_mov_b32_e32 v174, v170
	v_mov_b32_e32 v175, v171
	s_mov_b64 s[52:53], 0x58000
	v_lshl_add_u64 v[176:177], v[148:149], 0, s[52:53]
	s_mov_b64 s[52:53], 0x5c000
	v_lshl_add_u64 v[178:179], v[148:149], 0, s[52:53]
	v_mov_b32_dpp v168, v164 row_ror:8 row_mask:0xf bank_mask:0x3
	v_mov_b32_dpp v169, v165 row_ror:8 row_mask:0xf bank_mask:0x3
	v_mov_b32_dpp v170, v166 row_ror:8 row_mask:0xf bank_mask:0x3
	v_mov_b32_dpp v171, v167 row_ror:8 row_mask:0xf bank_mask:0x3
	v_mov_b32_dpp v164, v172 row_ror:8 row_mask:0xf bank_mask:0xc
	v_mov_b32_dpp v165, v173 row_ror:8 row_mask:0xf bank_mask:0xc
	v_mov_b32_dpp v166, v174 row_ror:8 row_mask:0xf bank_mask:0xc
	v_mov_b32_dpp v167, v175 row_ror:8 row_mask:0xf bank_mask:0xc
	s_nop 0
	global_store_dwordx4 v[176:177], v[164:167], off
	global_store_dwordx4 v[178:179], v[168:171], off
	s_andn2_b64 vcc, exec, s[2:3]
	s_mov_b64 s[2:3], -1
	s_cbranch_vccnz .LBB0_793
	s_andn2_b64 vcc, exec, s[4:5]
	s_cbranch_vccnz .LBB0_792
	s_barrier
	s_branch .LBB0_792
